# GEMM bf16 epilogues (gemm0a, mix1): the 8 serialised LDS-read/store steps per half get their own register quads, reads issued together with counted waits
# speedup vs baseline: 1.0015x; 1.0015x over previous
.Lg16_nd1_gq:
	s_setprio 1
	v_mfma_f32_16x16x32_bf16 v[36:39], v[224:227], v[152:155], v[36:39]
	v_mfma_f32_16x16x32_bf16 v[40:43], v[228:231], v[152:155], v[40:43]
	v_mfma_f32_16x16x32_bf16 v[44:47], v[232:235], v[152:155], v[44:47]
	v_mfma_f32_16x16x32_bf16 v[48:51], v[236:239], v[152:155], v[48:51]
	v_mfma_f32_16x16x32_bf16 v[52:55], v[224:227], v[164:167], v[52:55]
	v_mfma_f32_16x16x32_bf16 v[56:59], v[228:231], v[164:167], v[56:59]
	v_mfma_f32_16x16x32_bf16 v[60:63], v[232:235], v[164:167], v[60:63]
	v_mfma_f32_16x16x32_bf16 v[64:67], v[236:239], v[164:167], v[64:67]
	v_mfma_f32_16x16x32_bf16 v[4:7], v[224:227], v[168:171], v[4:7]
	v_mfma_f32_16x16x32_bf16 v[8:11], v[228:231], v[168:171], v[8:11]
	v_mfma_f32_16x16x32_bf16 v[12:15], v[232:235], v[168:171], v[12:15]
	v_mfma_f32_16x16x32_bf16 v[16:19], v[236:239], v[168:171], v[16:19]
	v_mfma_f32_16x16x32_bf16 v[20:23], v[224:227], v[212:215], v[20:23]
	v_mfma_f32_16x16x32_bf16 v[24:27], v[228:231], v[212:215], v[24:27]
	v_mfma_f32_16x16x32_bf16 v[28:31], v[232:235], v[212:215], v[28:31]
	v_mfma_f32_16x16x32_bf16 v[32:35], v[236:239], v[212:215], v[32:35]
	s_setprio 0
	s_add_u32 s0, s0, 1
	s_cmp_lt_u32 s0, 16
	s_cbranch_scc1 .Lg16_loop_gq
	s_nop 7
	s_and_b32 s0, s47, -4
	s_cmp_lg_u32 s0, 8
	s_cselect_b64 s[0:1], -1, 0
	s_add_i32 s2, s46, 0xfffffe00
	s_nop 5
	s_barrier
	s_cmp_lt_i32 s47, 8
	s_cselect_b32 s2, s46, s2
	v_or_b32_e32 v134, s2, v206
	v_and_b32_e32 v145, 63, v160
	v_lshrrev_b32_e32 v146, 6, v160
	v_and_b32_e32 v147, 15, v145
	v_lshrrev_b32_e32 v145, 4, v145
	v_mul_u32_u24_e32 v147, 0x90, v147
	v_lshl_add_u32 v147, v145, 3, v147
	v_mul_u32_u24_e32 v146, 0x2400, v146
	v_add_u32_e32 v144, v147, v146
	v_cvt_pk_bf16_f32 v136, v100, v101
	v_cvt_pk_bf16_f32 v137, v102, v103
	ds_write_b64 v144, v[136:137]
	v_cvt_pk_bf16_f32 v138, v104, v105
	v_cvt_pk_bf16_f32 v139, v106, v107
	ds_write_b64 v144, v[138:139] offset:32
	v_cvt_pk_bf16_f32 v140, v108, v109
	v_cvt_pk_bf16_f32 v141, v110, v111
	ds_write_b64 v144, v[140:141] offset:64
	v_cvt_pk_bf16_f32 v142, v112, v113
	v_cvt_pk_bf16_f32 v143, v114, v115
	ds_write_b64 v144, v[142:143] offset:96
	v_cvt_pk_bf16_f32 v136, v116, v117
	v_cvt_pk_bf16_f32 v137, v118, v119
	ds_write_b64 v144, v[136:137] offset:2304
	v_cvt_pk_bf16_f32 v138, v120, v121
	v_cvt_pk_bf16_f32 v139, v122, v123
	ds_write_b64 v144, v[138:139] offset:2336
	v_cvt_pk_bf16_f32 v140, v124, v125
	v_cvt_pk_bf16_f32 v141, v126, v127
	ds_write_b64 v144, v[140:141] offset:2368
	v_cvt_pk_bf16_f32 v142, v128, v129
	v_cvt_pk_bf16_f32 v143, v130, v131
	ds_write_b64 v144, v[142:143] offset:2400
	v_cvt_pk_bf16_f32 v136, v68, v69
	v_cvt_pk_bf16_f32 v137, v70, v71
	ds_write_b64 v144, v[136:137] offset:4608
	v_cvt_pk_bf16_f32 v138, v72, v73
	v_cvt_pk_bf16_f32 v139, v74, v75
	ds_write_b64 v144, v[138:139] offset:4640
	v_cvt_pk_bf16_f32 v140, v76, v77
	v_cvt_pk_bf16_f32 v141, v78, v79
	ds_write_b64 v144, v[140:141] offset:4672
	v_cvt_pk_bf16_f32 v142, v80, v81
	v_cvt_pk_bf16_f32 v143, v82, v83
	ds_write_b64 v144, v[142:143] offset:4704
	v_cvt_pk_bf16_f32 v136, v84, v85
	v_cvt_pk_bf16_f32 v137, v86, v87
	ds_write_b64 v144, v[136:137] offset:6912
	v_cvt_pk_bf16_f32 v138, v88, v89
	v_cvt_pk_bf16_f32 v139, v90, v91
	ds_write_b64 v144, v[138:139] offset:6944
	v_cvt_pk_bf16_f32 v140, v92, v93
	v_cvt_pk_bf16_f32 v141, v94, v95
	ds_write_b64 v144, v[140:141] offset:6976
	v_cvt_pk_bf16_f32 v142, v96, v97
	v_cvt_pk_bf16_f32 v143, v98, v99
	ds_write_b64 v144, v[142:143] offset:7008
	s_waitcnt lgkmcnt(0)
	v_ashrrev_i32_e32 v135, 31, v134
	v_add_u32_e32 v132, s48, v161
	s_mov_b64 s[2:3], -1
	s_and_b64 vcc, exec, s[0:1]
	v_lshlrev_b64 v[82:83], 1, v[134:135]
	s_cbranch_vccz .LBB0_123
	ds_read_b128 v[84:87], v210
	ds_read_b128 v[88:91], v210 offset:1152
	ds_read_b128 v[92:95], v210 offset:2304
	ds_read_b128 v[96:99], v210 offset:3456
	ds_read_b128 v[100:103], v210 offset:4608
	ds_read_b128 v[104:107], v210 offset:5760
	ds_read_b128 v[108:111], v210 offset:6912
	ds_read_b128 v[112:115], v210 offset:8064
	v_readlane_b32 s4, v254, 62
	v_readlane_b32 s18, v255, 12
	v_readlane_b32 s19, v255, 13
	v_or_b32_e32 v74, v132, v172
	v_readlane_b32 s5, v254, 63
	v_mov_b64_e32 v[72:73], s[18:19]
	v_mad_i64_i32 v[74:75], s[2:3], v74, s51, v[72:73]
	v_lshl_add_u64 v[74:75], v[74:75], 0, v[82:83]
	s_waitcnt lgkmcnt(7)
	global_store_dwordx4 v[74:75], v[84:87], off
	v_or_b32_e32 v74, v132, v176
	v_mad_i64_i32 v[74:75], s[2:3], v74, s51, v[72:73]
	v_lshl_add_u64 v[74:75], v[74:75], 0, v[82:83]
	s_waitcnt lgkmcnt(6)
	global_store_dwordx4 v[74:75], v[88:91], off
	v_or_b32_e32 v74, v132, v178
	v_mad_i64_i32 v[74:75], s[2:3], v74, s51, v[72:73]
	v_lshl_add_u64 v[74:75], v[74:75], 0, v[82:83]
	s_waitcnt lgkmcnt(5)
	global_store_dwordx4 v[74:75], v[92:95], off
	v_or_b32_e32 v74, v132, v179
	v_mad_i64_i32 v[74:75], s[2:3], v74, s51, v[72:73]
	v_lshl_add_u64 v[74:75], v[74:75], 0, v[82:83]
	s_waitcnt lgkmcnt(4)
	global_store_dwordx4 v[74:75], v[96:99], off
	v_or_b32_e32 v74, v132, v180
	v_mad_i64_i32 v[74:75], s[2:3], v74, s51, v[72:73]
	v_lshl_add_u64 v[74:75], v[74:75], 0, v[82:83]
	s_waitcnt lgkmcnt(3)
	global_store_dwordx4 v[74:75], v[100:103], off
	v_or_b32_e32 v74, v132, v181
	v_mad_i64_i32 v[74:75], s[2:3], v74, s51, v[72:73]
	v_lshl_add_u64 v[74:75], v[74:75], 0, v[82:83]
	s_waitcnt lgkmcnt(2)
	global_store_dwordx4 v[74:75], v[104:107], off
	v_or_b32_e32 v74, v132, v202
	v_mad_i64_i32 v[74:75], s[2:3], v74, s51, v[72:73]
	v_lshl_add_u64 v[74:75], v[74:75], 0, v[82:83]
	s_waitcnt lgkmcnt(1)
	global_store_dwordx4 v[74:75], v[108:111], off
	v_or_b32_e32 v74, v132, v203
	v_mad_i64_i32 v[72:73], s[2:3], v74, s51, v[72:73]
	v_lshl_add_u64 v[72:73], v[72:73], 0, v[82:83]
	s_mov_b64 s[2:3], 0
	v_readlane_b32 s6, v255, 0
	v_readlane_b32 s7, v255, 1
	v_readlane_b32 s8, v255, 2
	v_readlane_b32 s9, v255, 3
	v_readlane_b32 s10, v255, 4
	v_readlane_b32 s11, v255, 5
	v_readlane_b32 s12, v255, 6
	v_readlane_b32 s13, v255, 7
	v_readlane_b32 s14, v255, 8
	v_readlane_b32 s15, v255, 9
	v_readlane_b32 s16, v255, 10
	v_readlane_b32 s17, v255, 11
	s_waitcnt lgkmcnt(0)
	global_store_dwordx4 v[72:73], v[112:115], off

.LBB0_125:
	s_waitcnt lgkmcnt(0)
	v_and_b32_e32 v145, 63, v160
	v_lshrrev_b32_e32 v146, 6, v160
	v_and_b32_e32 v147, 15, v145
	v_lshrrev_b32_e32 v145, 4, v145
	v_mul_u32_u24_e32 v147, 0x90, v147
	v_lshl_add_u32 v147, v145, 3, v147
	v_mul_u32_u24_e32 v146, 0x2400, v146
	v_add_u32_e32 v144, v147, v146
	v_cvt_pk_bf16_f32 v136, v36, v37
	v_cvt_pk_bf16_f32 v137, v38, v39
	ds_write_b64 v144, v[136:137]
	v_cvt_pk_bf16_f32 v138, v40, v41
	v_cvt_pk_bf16_f32 v139, v42, v43
	ds_write_b64 v144, v[138:139] offset:32
	v_cvt_pk_bf16_f32 v140, v44, v45
	v_cvt_pk_bf16_f32 v141, v46, v47
	ds_write_b64 v144, v[140:141] offset:64
	v_cvt_pk_bf16_f32 v142, v48, v49
	v_cvt_pk_bf16_f32 v143, v50, v51
	ds_write_b64 v144, v[142:143] offset:96
	v_cvt_pk_bf16_f32 v136, v52, v53
	v_cvt_pk_bf16_f32 v137, v54, v55
	ds_write_b64 v144, v[136:137] offset:2304
	v_cvt_pk_bf16_f32 v138, v56, v57
	v_cvt_pk_bf16_f32 v139, v58, v59
	ds_write_b64 v144, v[138:139] offset:2336
	v_cvt_pk_bf16_f32 v140, v60, v61
	v_cvt_pk_bf16_f32 v141, v62, v63
	ds_write_b64 v144, v[140:141] offset:2368
	v_cvt_pk_bf16_f32 v142, v64, v65
	v_cvt_pk_bf16_f32 v143, v66, v67
	ds_write_b64 v144, v[142:143] offset:2400
	v_cvt_pk_bf16_f32 v136, v4, v5
	v_cvt_pk_bf16_f32 v137, v6, v7
	ds_write_b64 v144, v[136:137] offset:4608
	v_cvt_pk_bf16_f32 v138, v8, v9
	v_cvt_pk_bf16_f32 v139, v10, v11
	ds_write_b64 v144, v[138:139] offset:4640
	v_cvt_pk_bf16_f32 v140, v12, v13
	v_cvt_pk_bf16_f32 v141, v14, v15
	ds_write_b64 v144, v[140:141] offset:4672
	v_cvt_pk_bf16_f32 v142, v16, v17
	v_cvt_pk_bf16_f32 v143, v18, v19
	ds_write_b64 v144, v[142:143] offset:4704
	v_cvt_pk_bf16_f32 v136, v20, v21
	v_cvt_pk_bf16_f32 v137, v22, v23
	ds_write_b64 v144, v[136:137] offset:6912
	v_cvt_pk_bf16_f32 v138, v24, v25
	v_cvt_pk_bf16_f32 v139, v26, v27
	ds_write_b64 v144, v[138:139] offset:6944
	v_cvt_pk_bf16_f32 v140, v28, v29
	v_cvt_pk_bf16_f32 v141, v30, v31
	ds_write_b64 v144, v[140:141] offset:6976
	v_cvt_pk_bf16_f32 v142, v32, v33
	v_cvt_pk_bf16_f32 v143, v34, v35
	ds_write_b64 v144, v[142:143] offset:7008
	s_waitcnt lgkmcnt(0)
	v_or_b32_e32 v4, 64, v132
	s_andn2_b64 vcc, exec, s[0:1]
	s_mov_b64 s[0:1], -1
	s_cbranch_vccnz .LBB0_127
	ds_read_b128 v[36:39], v210
	ds_read_b128 v[40:43], v210 offset:1152
	ds_read_b128 v[44:47], v210 offset:2304
	ds_read_b128 v[48:51], v210 offset:3456
	ds_read_b128 v[52:55], v210 offset:4608
	ds_read_b128 v[56:59], v210 offset:5760
	ds_read_b128 v[60:63], v210 offset:6912
	ds_read_b128 v[64:67], v210 offset:8064
	v_readlane_b32 s0, v254, 62
	v_readlane_b32 s14, v255, 12
	v_readlane_b32 s15, v255, 13
	v_or_b32_e32 v5, v4, v172
	v_readlane_b32 s1, v254, 63
	v_mov_b64_e32 v[10:11], s[14:15]
	v_mad_i64_i32 v[12:13], s[0:1], v5, s51, v[10:11]
	v_lshl_add_u64 v[12:13], v[12:13], 0, v[82:83]
	s_waitcnt lgkmcnt(7)
	global_store_dwordx4 v[12:13], v[36:39], off
	v_or_b32_e32 v5, v4, v176
	v_mad_i64_i32 v[12:13], s[0:1], v5, s51, v[10:11]
	v_lshl_add_u64 v[12:13], v[12:13], 0, v[82:83]
	s_waitcnt lgkmcnt(6)
	global_store_dwordx4 v[12:13], v[40:43], off
	v_or_b32_e32 v5, v4, v178
	v_mad_i64_i32 v[12:13], s[0:1], v5, s51, v[10:11]
	v_lshl_add_u64 v[12:13], v[12:13], 0, v[82:83]
	s_waitcnt lgkmcnt(5)
	global_store_dwordx4 v[12:13], v[44:47], off
	v_or_b32_e32 v5, v4, v179
	v_mad_i64_i32 v[12:13], s[0:1], v5, s51, v[10:11]
	v_lshl_add_u64 v[12:13], v[12:13], 0, v[82:83]
	s_waitcnt lgkmcnt(4)
	global_store_dwordx4 v[12:13], v[48:51], off
	v_or_b32_e32 v5, v4, v180
	v_mad_i64_i32 v[12:13], s[0:1], v5, s51, v[10:11]
	v_lshl_add_u64 v[12:13], v[12:13], 0, v[82:83]
	s_waitcnt lgkmcnt(3)
	global_store_dwordx4 v[12:13], v[52:55], off
	v_or_b32_e32 v5, v4, v181
	v_mad_i64_i32 v[12:13], s[0:1], v5, s51, v[10:11]
	v_lshl_add_u64 v[12:13], v[12:13], 0, v[82:83]
	s_waitcnt lgkmcnt(2)
	global_store_dwordx4 v[12:13], v[56:59], off
	v_or_b32_e32 v5, v4, v202
	v_mad_i64_i32 v[12:13], s[0:1], v5, s51, v[10:11]
	v_lshl_add_u64 v[12:13], v[12:13], 0, v[82:83]
	s_waitcnt lgkmcnt(1)
	global_store_dwordx4 v[12:13], v[60:63], off
	v_or_b32_e32 v5, v4, v203
	v_mad_i64_i32 v[10:11], s[0:1], v5, s51, v[10:11]
	v_lshl_add_u64 v[10:11], v[10:11], 0, v[82:83]
	s_mov_b64 s[0:1], 0
	v_readlane_b32 s2, v255, 0
	v_readlane_b32 s3, v255, 1
	v_readlane_b32 s4, v255, 2
	v_readlane_b32 s5, v255, 3
	v_readlane_b32 s6, v255, 4
	v_readlane_b32 s7, v255, 5
	v_readlane_b32 s8, v255, 6
	v_readlane_b32 s9, v255, 7
	v_readlane_b32 s10, v255, 8
	v_readlane_b32 s11, v255, 9
	v_readlane_b32 s12, v255, 10
	v_readlane_b32 s13, v255, 11
	s_waitcnt lgkmcnt(0)
	global_store_dwordx4 v[10:11], v[64:67], off

.Lg16_nd1_g0a:
	s_setprio 1
	v_mfma_f32_16x16x32_bf16 v[36:39], v[224:227], v[152:155], v[36:39]
	v_mfma_f32_16x16x32_bf16 v[40:43], v[228:231], v[152:155], v[40:43]
	v_mfma_f32_16x16x32_bf16 v[44:47], v[232:235], v[152:155], v[44:47]
	v_mfma_f32_16x16x32_bf16 v[48:51], v[236:239], v[152:155], v[48:51]
	v_mfma_f32_16x16x32_bf16 v[52:55], v[224:227], v[164:167], v[52:55]
	v_mfma_f32_16x16x32_bf16 v[56:59], v[228:231], v[164:167], v[56:59]
	v_mfma_f32_16x16x32_bf16 v[60:63], v[232:235], v[164:167], v[60:63]
	v_mfma_f32_16x16x32_bf16 v[64:67], v[236:239], v[164:167], v[64:67]
	v_mfma_f32_16x16x32_bf16 v[4:7], v[224:227], v[168:171], v[4:7]
	v_mfma_f32_16x16x32_bf16 v[8:11], v[228:231], v[168:171], v[8:11]
	v_mfma_f32_16x16x32_bf16 v[12:15], v[232:235], v[168:171], v[12:15]
	v_mfma_f32_16x16x32_bf16 v[16:19], v[236:239], v[168:171], v[16:19]
	v_mfma_f32_16x16x32_bf16 v[20:23], v[224:227], v[212:215], v[20:23]
	v_mfma_f32_16x16x32_bf16 v[24:27], v[228:231], v[212:215], v[24:27]
	v_mfma_f32_16x16x32_bf16 v[28:31], v[232:235], v[212:215], v[28:31]
	v_mfma_f32_16x16x32_bf16 v[32:35], v[236:239], v[212:215], v[32:35]
	s_setprio 0
	s_add_u32 s0, s0, 1
	s_cmp_lt_u32 s0, 16
	s_cbranch_scc1 .Lg16_loop_g0a
	s_nop 7
	s_and_b32 s0, s48, -4
	s_cmp_lg_u32 s0, 8
	s_cselect_b64 s[0:1], -1, 0
	s_add_i32 s2, s46, 0xfffffe00
	s_nop 5
	s_barrier
	s_cmp_lt_i32 s47, -8
	s_cselect_b32 s2, s46, s2
	v_or_b32_e32 v134, s2, v206
	v_and_b32_e32 v145, 63, v160
	v_lshrrev_b32_e32 v146, 6, v160
	v_and_b32_e32 v147, 15, v145
	v_lshrrev_b32_e32 v145, 4, v145
	v_mul_u32_u24_e32 v147, 0x90, v147
	v_lshl_add_u32 v147, v145, 3, v147
	v_mul_u32_u24_e32 v146, 0x2400, v146
	v_add_u32_e32 v144, v147, v146
	v_cvt_pk_bf16_f32 v136, v100, v101
	v_cvt_pk_bf16_f32 v137, v102, v103
	ds_write_b64 v144, v[136:137]
	v_cvt_pk_bf16_f32 v138, v104, v105
	v_cvt_pk_bf16_f32 v139, v106, v107
	ds_write_b64 v144, v[138:139] offset:32
	v_cvt_pk_bf16_f32 v140, v108, v109
	v_cvt_pk_bf16_f32 v141, v110, v111
	ds_write_b64 v144, v[140:141] offset:64
	v_cvt_pk_bf16_f32 v142, v112, v113
	v_cvt_pk_bf16_f32 v143, v114, v115
	ds_write_b64 v144, v[142:143] offset:96
	v_cvt_pk_bf16_f32 v136, v116, v117
	v_cvt_pk_bf16_f32 v137, v118, v119
	ds_write_b64 v144, v[136:137] offset:2304
	v_cvt_pk_bf16_f32 v138, v120, v121
	v_cvt_pk_bf16_f32 v139, v122, v123
	ds_write_b64 v144, v[138:139] offset:2336
	v_cvt_pk_bf16_f32 v140, v124, v125
	v_cvt_pk_bf16_f32 v141, v126, v127
	ds_write_b64 v144, v[140:141] offset:2368
	v_cvt_pk_bf16_f32 v142, v128, v129
	v_cvt_pk_bf16_f32 v143, v130, v131
	ds_write_b64 v144, v[142:143] offset:2400
	v_cvt_pk_bf16_f32 v136, v68, v69
	v_cvt_pk_bf16_f32 v137, v70, v71
	ds_write_b64 v144, v[136:137] offset:4608
	v_cvt_pk_bf16_f32 v138, v72, v73
	v_cvt_pk_bf16_f32 v139, v74, v75
	ds_write_b64 v144, v[138:139] offset:4640
	v_cvt_pk_bf16_f32 v140, v76, v77
	v_cvt_pk_bf16_f32 v141, v78, v79
	ds_write_b64 v144, v[140:141] offset:4672
	v_cvt_pk_bf16_f32 v142, v80, v81
	v_cvt_pk_bf16_f32 v143, v82, v83
	ds_write_b64 v144, v[142:143] offset:4704
	v_cvt_pk_bf16_f32 v136, v84, v85
	v_cvt_pk_bf16_f32 v137, v86, v87
	ds_write_b64 v144, v[136:137] offset:6912
	v_cvt_pk_bf16_f32 v138, v88, v89
	v_cvt_pk_bf16_f32 v139, v90, v91
	ds_write_b64 v144, v[138:139] offset:6944
	v_cvt_pk_bf16_f32 v140, v92, v93
	v_cvt_pk_bf16_f32 v141, v94, v95
	ds_write_b64 v144, v[140:141] offset:6976
	v_cvt_pk_bf16_f32 v142, v96, v97
	v_cvt_pk_bf16_f32 v143, v98, v99
	ds_write_b64 v144, v[142:143] offset:7008
	s_waitcnt lgkmcnt(0)
	v_ashrrev_i32_e32 v135, 31, v134
	v_add_u32_e32 v132, s49, v161
	s_mov_b64 s[2:3], -1
	s_and_b64 vcc, exec, s[0:1]
	v_lshlrev_b64 v[82:83], 1, v[134:135]
	s_cbranch_vccz .LBB0_244
	ds_read_b128 v[84:87], v210
	ds_read_b128 v[88:91], v210 offset:1152
	ds_read_b128 v[92:95], v210 offset:2304
	ds_read_b128 v[96:99], v210 offset:3456
	ds_read_b128 v[100:103], v210 offset:4608
	ds_read_b128 v[104:107], v210 offset:5760
	ds_read_b128 v[108:111], v210 offset:6912
	ds_read_b128 v[112:115], v210 offset:8064
	v_readlane_b32 s4, v254, 62
	v_readlane_b32 s18, v255, 12
	v_readlane_b32 s19, v255, 13
	v_or_b32_e32 v74, v132, v172
	v_readlane_b32 s5, v254, 63
	v_mov_b64_e32 v[72:73], s[18:19]
	v_mad_i64_i32 v[74:75], s[2:3], v74, s51, v[72:73]
	v_lshl_add_u64 v[74:75], v[74:75], 0, v[82:83]
	s_waitcnt lgkmcnt(7)
	global_store_dwordx4 v[74:75], v[84:87], off
	v_or_b32_e32 v74, v132, v176
	v_mad_i64_i32 v[74:75], s[2:3], v74, s51, v[72:73]
	v_lshl_add_u64 v[74:75], v[74:75], 0, v[82:83]
	s_waitcnt lgkmcnt(6)
	global_store_dwordx4 v[74:75], v[88:91], off
	v_or_b32_e32 v74, v132, v178
	v_mad_i64_i32 v[74:75], s[2:3], v74, s51, v[72:73]
	v_lshl_add_u64 v[74:75], v[74:75], 0, v[82:83]
	s_waitcnt lgkmcnt(5)
	global_store_dwordx4 v[74:75], v[92:95], off
	v_or_b32_e32 v74, v132, v179
	v_mad_i64_i32 v[74:75], s[2:3], v74, s51, v[72:73]
	v_lshl_add_u64 v[74:75], v[74:75], 0, v[82:83]
	s_waitcnt lgkmcnt(4)
	global_store_dwordx4 v[74:75], v[96:99], off
	v_or_b32_e32 v74, v132, v180
	v_mad_i64_i32 v[74:75], s[2:3], v74, s51, v[72:73]
	v_lshl_add_u64 v[74:75], v[74:75], 0, v[82:83]
	s_waitcnt lgkmcnt(3)
	global_store_dwordx4 v[74:75], v[100:103], off
	v_or_b32_e32 v74, v132, v181
	v_mad_i64_i32 v[74:75], s[2:3], v74, s51, v[72:73]
	v_lshl_add_u64 v[74:75], v[74:75], 0, v[82:83]
	s_waitcnt lgkmcnt(2)
	global_store_dwordx4 v[74:75], v[104:107], off
	v_or_b32_e32 v74, v132, v202
	v_mad_i64_i32 v[74:75], s[2:3], v74, s51, v[72:73]
	v_lshl_add_u64 v[74:75], v[74:75], 0, v[82:83]
	s_waitcnt lgkmcnt(1)
	global_store_dwordx4 v[74:75], v[108:111], off
	v_or_b32_e32 v74, v132, v203
	v_mad_i64_i32 v[72:73], s[2:3], v74, s51, v[72:73]
	v_lshl_add_u64 v[72:73], v[72:73], 0, v[82:83]
	s_mov_b64 s[2:3], 0
	v_readlane_b32 s6, v255, 0
	v_readlane_b32 s7, v255, 1
	v_readlane_b32 s8, v255, 2
	v_readlane_b32 s9, v255, 3
	v_readlane_b32 s10, v255, 4
	v_readlane_b32 s11, v255, 5
	v_readlane_b32 s12, v255, 6
	v_readlane_b32 s13, v255, 7
	v_readlane_b32 s14, v255, 8
	v_readlane_b32 s15, v255, 9
	v_readlane_b32 s16, v255, 10
	v_readlane_b32 s17, v255, 11
	s_waitcnt lgkmcnt(0)
	global_store_dwordx4 v[72:73], v[112:115], off
